# GDN scan start-up: decay-table load no longer waited before the three chunk prefetches are issued
# speedup vs baseline: 1.0010x; 1.0010x over previous
; DI int otid() { int t = threadIdx.x; asm volatile("" : "+v"(t)); return t; }
; DI void gdn_scan_item(const P& p, int item, unsigned char* smem) {
;     const int seq = (item & 7) * 4 + (item >> 5), cq = (item >> 3) & 3;
;     const int dir = seq >> 4, b = (seq >> 2) & 3, h = seq & 3;
;     constexpr int BUFB = 3 * 17408 + 9216 + 5120;
;     bf16_t* sVN = (bf16_t*)(smem + 2 * BUFB);
;     float* sdec = (float*)(smem + 2 * BUFB + 5120);
;     const bf16_t* U = (const bf16_t*)(p.ws + WS_GDN_U); const bf16_t* W = (const bf16_t*)(p.ws + WS_GDN_W); const bf16_t* QI = (const bf16_t*)(p.ws + WS_GDN_QI); const bf16_t* KO = (const bf16_t*)(p.ws + WS_GDN_KO);
;     const bf16_t* AT = (const bf16_t*)(p.ws + WS_GDN_AT); const float* DC = (const float*)(p.ws + WS_GDN_DC);
;     bf16_t* OG = (bf16_t*)(p.ws + WS_NBUF) + (size_t)(2 + dir) * NROW * 512;
;     const int tid = otid(), w = tid >> 6, lane = tid & 63, l15 = lane & 15, g = lane >> 4, q4 = l15 >> 2, p4 = l15 & 3;
;     const int mt = w >> 1, nt = w & 1;
;     auto loadr = [&](GdnRegs& R, int c) {
;         if (c >= 36) return;
;         u32x4* rr = R.r;
; #pragma unroll
;         for (int k = 0; k < 2; ++k) {
;             const int e = tid + 512 * k, r = e >> 4, ch = e & 15; const size_t off = ((size_t)seq * PT + 64 * c + r) * 128 + 8 * ch;
;             rr[k] = *(const u32x4*)(W + off); rr[2 + k] = *(const u32x4*)(QI + off); rr[4 + k] = *(const u32x4*)(KO + off);
;         }
;         { const int r = tid >> 3, ch = tid & 7; rr[6] = *(const u32x4*)(AT + (((size_t)seq * 36 + c) * 64 + r) * 64 + 8 * ch); }
;         if (tid < 256) { const int r = tid >> 2, ch = tid & 3; rr[7] = __builtin_nontemporal_load((const u32x4*)(U + ((size_t)seq * PT + 64 * c + r) * 128 + 32 * cq + 8 * ch)); }
;     };
;     auto storel = [&](const GdnRegs& R, int buf) {
;         const u32x4* rr = R.r;
;         bf16_t* sW = (bf16_t*)(smem + buf * BUFB); bf16_t* sQI = sW + 64 * 136; bf16_t* sKO = sQI + 64 * 136; bf16_t* sAT = sKO + 64 * 136; bf16_t* sU = sAT + 64 * 72;
; #pragma unroll
;         for (int k = 0; k < 2; ++k) {
;             const int e = tid + 512 * k, r = e >> 4, ch = e & 15; const int off = r * 136 + 8 * ch;
;             *(u32x4*)(sW + off) = rr[k]; *(u32x4*)(sQI + off) = rr[2 + k]; *(u32x4*)(sKO + off) = rr[4 + k];
;         }
;         { const int r = tid >> 3, ch = tid & 7; *(u32x4*)(sAT + r * 72 + 8 * ch) = rr[6]; }
.LBB0_489:
	s_sub_i32 s0, s56, 32
	v_mov_b32_e32 v96, v166
	s_lshl_b32 s1, s0, 2
	s_lshr_b32 s24, s0, 5
	s_add_i32 s0, s57, 0x21d00
	s_and_b32 s22, s1, 28
	v_and_b32_e32 v110, 63, v96
	s_waitcnt vmcnt(39)
	v_ashrrev_i32_e32 v97, 7, v96
	v_bfe_u32 v105, v96, 6, 1
	v_lshl_add_u32 v111, v105, 12, s0
	v_lshlrev_b32_e32 v0, 10, v97
	v_lshlrev_b32_e32 v1, 4, v110
	s_or_b32 s2, s22, s24
	s_add_i32 s21, s57, 0x21c00
	v_add3_u32 v156, v111, v0, v1
	v_cmp_gt_i32_e32 vcc, 36, v96
	ds_write_b128 v156, v[220:223]
	s_and_saveexec_b64 s[0:1], vcc
	s_cbranch_execz .LBB0_491
	v_mad_u64_u32 v[0:1], s[4:5], s2, 36, v[96:97]
	v_ashrrev_i32_e32 v1, 31, v0
	v_lshl_add_u64 v[0:1], v[0:1], 2, s[46:47]
	v_add_co_u32_e32 v0, vcc, 0x17e4c000, v0
	s_nop 1
	v_addc_co_u32_e32 v1, vcc, 0, v1, vcc
	global_load_dword v216, v[0:1], off
	v_lshl_add_u32 v217, v96, 2, s21

; DI void gdn_scan_item(const P& p, int item, unsigned char* smem) {
;     ...
;     const int tid = otid(), w = tid >> 6, lane = tid & 63, l15 = lane & 15, g = lane >> 4, q4 = l15 >> 2, p4 = l15 & 3;
;     const int mt = w >> 1, nt = w & 1;
;     auto loadr = [&](GdnRegs& R, int c) {
;         if (c >= 36) return;
;         u32x4* rr = R.r;
; #pragma unroll
;         for (int k = 0; k < 2; ++k) {
;             const int e = tid + 512 * k, r = e >> 4, ch = e & 15; const size_t off = ((size_t)seq * PT + 64 * c + r) * 128 + 8 * ch;
;             rr[k] = *(const u32x4*)(W + off); rr[2 + k] = *(const u32x4*)(QI + off); rr[4 + k] = *(const u32x4*)(KO + off);
;         }
;         { const int r = tid >> 3, ch = tid & 7; rr[6] = *(const u32x4*)(AT + (((size_t)seq * 36 + c) * 64 + r) * 64 + 8 * ch); }
;         if (tid < 256) { const int r = tid >> 2, ch = tid & 3; rr[7] = __builtin_nontemporal_load((const u32x4*)(U + ((size_t)seq * PT + 64 * c + r) * 128 + 32 * cq + 8 * ch)); }
;     };
;     auto storel = [&](const GdnRegs& R, int buf) {
;         const u32x4* rr = R.r;
;         bf16_t* sW = (bf16_t*)(smem + buf * BUFB); bf16_t* sQI = sW + 64 * 136; bf16_t* sKO = sQI + 64 * 136; bf16_t* sAT = sKO + 64 * 136; bf16_t* sU = sAT + 64 * 72;
; #pragma unroll
;         for (int k = 0; k < 2; ++k) {
;             const int e = tid + 512 * k, r = e >> 4, ch = e & 15; const int off = r * 136 + 8 * ch;
;             *(u32x4*)(sW + off) = rr[k]; *(u32x4*)(sQI + off) = rr[2 + k]; *(u32x4*)(sKO + off) = rr[4 + k];
;         }
;         { const int r = tid >> 3, ch = tid & 7; *(u32x4*)(sAT + r * 72 + 8 * ch) = rr[6]; }
;         if (tid < 256) { const int r = tid >> 2, ch = tid & 3; *(u32x4*)(sU + r * 40 + 8 * ch) = rr[7]; }
;     };
;     u32x4* sBS = (u32x4*)(smem + 2 * BUFB + 5120 + 256);
;     f32x4 st[2];
;     st[0] = (f32x4){0.f, 0.f, 0.f, 0.f}; st[1] = (f32x4){0.f, 0.f, 0.f, 0.f};
;     sBS[(nt * 4 + mt) * 64 + lane] = (u32x4){0u, 0u, 0u, 0u};
;     if (tid < 36) sdec[tid] = DC[seq * 36 + tid];
;     const int sgn = dir ? -1 : 1;
;     auto step = [&](GdnRegs& R, int c) {
;         storel(R, c & 1);
;         __syncthreads();
;         loadr(R, c + 3);
;         const bf16_t* sW = (const bf16_t*)(smem + (c & 1) * BUFB); const bf16_t* sQI = sW + 64 * 136; const bf16_t* sKO = sQI + 64 * 136; const bf16_t* sAT = sKO + 64 * 136; const bf16_t* sU = sAT + 64 * 72;
.LBB0_499:
	s_or_b64 exec, exec, s[38:39]
	s_lshr_b32 s2, s22, 4
	s_and_b32 s3, s56, 3
	s_add_i32 s6, s57, 0x20800
	s_mul_i32 s2, s2, 0x900000
	s_add_u32 s2, s46, s2
	s_addc_u32 s4, s47, 0
	s_cmp_lt_u32 s22, 16
	s_cselect_b64 s[38:39], -1, 0
	s_lshl_b32 s5, s24, 8
	s_add_u32 s7, s2, s5
	s_movk_i32 s9, 0x88
	s_addc_u32 s8, s4, 0
	v_mad_u64_u32 v[120:121], s[4:5], v98, s9, v[132:133]
	v_mad_u64_u32 v[122:123], s[4:5], v100, s9, v[132:133]
	v_and_b32_e32 v108, 15, v96
	s_movk_i32 s4, 0x48
	v_lshrrev_b32_e32 v112, 4, v110
	v_mul_lo_u32 v114, v106, s4
	v_lshl_add_u32 v117, v110, 4, v111
	v_lshl_or_b32 v110, v97, 4, v108
	s_movk_i32 s4, 0x50
	v_lshlrev_b32_e32 v132, 5, v105
	v_lshlrev_b32_e32 v115, 4, v105
	v_mul_lo_u32 v106, v110, s4
	v_lshlrev_b32_e32 v124, 3, v112
	v_add_u32_e32 v105, s6, v132
	v_add3_u32 v123, v105, v106, v124
	v_lshlrev_b32_e32 v106, 2, v96
	v_bfe_u32 v113, v96, 2, 2
	v_and_b32_e32 v157, 12, v106
	v_lshlrev_b32_e32 v107, 13, v97
	v_lshlrev_b32_e32 v111, 2, v112
	v_lshl_add_u32 v112, v157, 1, v105
	v_or_b32_e32 v105, 4, v113
	v_lshl_or_b32 v107, v108, 9, v107
	s_lshl_b32 s2, s3, 11
	s_lshl_b32 s3, s3, 8
	v_or_b32_e32 v106, v124, v105
	v_sub_u32_e32 v109, 0, v107
	s_bitset1_b32 s3, 13
	v_mul_u32_u24_e32 v150, 0x50, v106
	v_or_b32_e32 v106, 32, v124
	v_or_b32_e32 v134, v124, v113
	v_or_b32_e32 v113, v106, v113
	v_or_b32_e32 v105, v106, v105
	s_add_u32 s4, s7, s26
	v_cndmask_b32_e64 v106, v109, v107, s[38:39]
	s_addc_u32 s5, s8, 0
	v_ashrrev_i32_e32 v107, 31, v106
	v_lshl_add_u64 v[106:107], v[106:107], 1, s[4:5]
	v_lshl_add_u64 v[106:107], v[106:107], 0, v[132:133]
	v_mov_b32_e32 v125, v133
	v_lshl_add_u64 v[106:107], v[106:107], 0, v[124:125]
	s_mov_b64 s[4:5], 0x5a3c000
	v_lshl_add_u64 v[126:127], v[106:107], 0, s[4:5]
	s_movk_i32 s4, 0xff40
	v_mul_lo_u32 v158, v110, s4
	s_movk_i32 s4, 0xc0
	s_add_i32 s24, s24, s22
	v_and_b32_e32 v96, 7, v96
	v_mul_lo_u32 v121, v110, s9
	v_lshlrev_b32_e32 v125, 5, v97
	v_mul_lo_u32 v159, v110, s4
	v_lshlrev_b32_e32 v97, 7, v110
	v_mad_u64_u32 v[102:103], s[4:5], s24, v181, v[102:103]
	v_lshlrev_b32_e32 v132, 4, v96
	v_readlane_b32 s8, v254, 26
	v_mul_u32_u24_e32 v152, 0x50, v105
	v_ashrrev_i32_e32 v105, 31, v104
	v_sub_u32_e32 v160, 0, v97
	v_lshl_add_u64 v[96:97], v[102:103], 0, v[132:133]
	v_readlane_b32 s9, v254, 27
	v_mul_u32_u24_e32 v135, 0x50, v134
	v_mul_u32_u24_e32 v151, 0x50, v113
	v_lshl_add_u64 v[142:143], s[8:9], 0, v[96:97]
	v_lshlrev_b64 v[96:97], 8, v[104:105]
	v_mad_u64_u32 v[96:97], s[4:5], s24, v182, v[96:97]
	s_lshl_b32 s4, s56, 3
	s_and_b32 s4, s4, 0xc0
	v_or_b32_e32 v96, s4, v96
	v_lshl_add_u64 v[96:97], v[118:119], 1, v[96:97]
	v_lshl_add_u64 v[144:145], s[8:9], 0, v[96:97]
	v_lshlrev_b64 v[96:97], 8, v[100:101]
	v_mad_u64_u32 v[96:97], s[4:5], s24, v182, v[96:97]
	v_lshlrev_b32_e32 v100, 4, v108
	v_or_b32_e32 v96, v96, v100
	v_lshl_add_u64 v[146:147], s[8:9], 0, v[96:97]
	v_lshlrev_b64 v[96:97], 8, v[98:99]
	v_mad_u64_u32 v[96:97], s[4:5], s24, v182, v[96:97]
	v_or_b32_e32 v96, v96, v100
	v_mul_u32_u24_e32 v106, 0x88, v134
	v_mul_u32_u24_e32 v107, 0x88, v113
	v_mul_lo_u32 v109, v104, 40
	v_lshl_add_u64 v[148:149], s[8:9], 0, v[96:97]
	v_mov_b32_e32 v96, 0
	s_mov_b32 s27, -3
	s_movk_i32 s22, 0x80
	s_movk_i32 s24, 0x87f
	v_lshlrev_b32_e32 v119, 1, v114
	v_lshlrev_b32_e32 v161, 1, v109
	v_lshlrev_b32_e32 v162, 1, v111
	v_lshlrev_b32_e32 v163, 1, v115
	v_add_u32_e32 v164, v112, v135
	v_add_u32_e32 v165, v112, v150
	v_add_u32_e32 v183, v112, v151
	v_add_u32_e32 v184, v112, v152
	v_lshlrev_b32_e32 v185, 1, v106
	v_lshlrev_b32_e32 v186, 1, v107
	v_mov_b32_e32 v97, v96
	v_mov_b32_e32 v98, v96
	v_mov_b32_e32 v99, v96
	v_mov_b32_e32 v100, v96
	v_mov_b32_e32 v101, v96
	v_mov_b32_e32 v102, v96
	v_mov_b32_e32 v103, v96
	v_readlane_b32 s10, v254, 28
	v_readlane_b32 s11, v254, 29
	v_cmp_gt_i32_e64 s[98:99], 36, v166
	s_nop 1
	s_and_saveexec_b64 s[100:101], s[98:99]
	s_waitcnt vmcnt(20)
	ds_write_b32 v217, v216
	s_mov_b64 exec, s[100:101]
	s_branch .LBB0_501
